# bias the m3 work queue: workgroups with 3 gates tiles stop pulling m3 items near the queue end (static heavy/light balancing)
# speedup vs baseline: 1.0012x; 1.0012x over previous
.LBB0_5:
	s_or_b64 exec, exec, s[4:5]
	s_lshr_b32 s3, s3, 6
	s_mov_b32 s4, 0
	v_writelane_b32 v255, s4, 57
	s_mov_b64 s[16:17], s[76:77]
	s_mov_b32 s4, -1
	s_mov_b32 s5, s3
	s_mov_b32 s33, s96
	v_mbcnt_lo_u32_b32 v2, s4, 0
	v_mbcnt_hi_u32_b32 v2, s4, v2
	v_lshl_add_u32 v140, s5, 6, v2
	s_load_dwordx2 s[14:15], s[16:17], 0xb8
	s_lshl_b32 s4, s2, 9
	v_add_u32_e32 v138, s4, v140
	v_writelane_b32 v255, s4, 0
	s_mov_b32 s4, 0x10000
	v_cmp_gt_i32_e64 s[8:9], s4, v138
	v_ashrrev_i32_e32 v139, 31, v138
	s_and_saveexec_b64 s[18:19], s[8:9]
	s_cbranch_execz .LBB0_20
	v_and_b32_e32 v2, 15, v140
	v_cvt_f32_ubyte0_e32 v2, v2
	v_mul_f32_e32 v3, 0xbf549a78, v2
	s_mov_b32 s4, 0xc2fc0000
	v_mov_b32_e32 v4, 0x42800000
	v_cmp_gt_f32_e32 vcc, s4, v3
	v_not_b32_e32 v6, 63
	s_lshl_b32 s20, s33, 9
	v_cndmask_b32_e32 v3, 0, v4, vcc
	v_fmac_f32_e32 v3, 0xbf549a78, v2
	v_exp_f32_e32 v2, v3
	v_cndmask_b32_e32 v3, 0, v6, vcc
	s_mov_b64 s[4:5], 0x180000
	s_ashr_i32 s21, s20, 31
	v_ldexp_f32 v7, v2, v3
	s_waitcnt lgkmcnt(0)
	v_lshl_add_u64 v[2:3], v[138:139], 2, s[14:15]
	v_lshl_add_u64 v[2:3], v[2:3], 0, s[4:5]
	s_lshl_b64 s[24:25], s[20:21], 2
	s_mov_b64 s[26:27], 0
	s_brev_b32 s21, 18
	s_mov_b32 s23, 0xfe5163ab
	v_mov_b32_e32 v5, 0
	s_mov_b32 s30, 0x3c439041
	s_mov_b32 s31, 0xdb629599
	s_mov_b32 s34, 0xf534ddc0
	s_mov_b32 s35, 0xfc2757d1
	s_mov_b32 s36, 0x4e441529
	s_mov_b32 s37, 0xa2f9836e
	s_mov_b32 s38, 0x3fc90fda
	s_mov_b32 s39, 0x3f22f983
	s_mov_b32 s40, 0xbfc90fda
	v_mov_b32_e32 v8, 0x3c0881c4
	v_mov_b32_e32 v9, 0xbab64f3b
	s_brev_b32 s41, 1
	s_movk_i32 s42, 0x1f8
	s_mov_b32 s43, 0xffff
	v_not_b32_e32 v10, 31
	v_mov_b32_e32 v11, 0x7fc00000
	v_mov_b32_e32 v12, v138
	s_branch .LBB0_8

.LBB0_1223:
	v_readlane_b32 s4, v255, 57
	s_cmp_lg_u32 s4, 0
	s_cbranch_scc0 .Lhl_cont
	s_mov_b32 s4, 0
	v_writelane_b32 v255, s4, 57
	s_mov_b64 s[4:5], -1
	s_branch .LBB0_1222

.LBB0_1227:
	s_or_b64 exec, exec, s[4:5]
	v_mov_b32_e32 v0, s59
	s_waitcnt lgkmcnt(0)
	s_barrier
	ds_read_b32 v0, v0
	s_mov_b64 s[4:5], -1
	s_waitcnt lgkmcnt(0)
	v_cmp_le_i32_e32 vcc, s37, v0
	v_readfirstlane_b32 s63, v0
	s_cbranch_vccnz .LBB0_1222
	s_mov_b32 s98, 0
	s_cmpk_lg_i32 s96, 0x100
	s_cbranch_scc1 .Lhl_set
	v_readlane_b32 s98, v255, 26
	s_cmp_eq_u32 s98, -1
	s_movk_i32 s98, 128
	s_cselect_b32 s98, 208, s98
	s_movk_i32 s99, 230
	s_cselect_b32 s99, 86, s99
	s_cmp_lt_i32 s2, s98
	s_cselect_b32 s98, 1, 0
	s_sub_i32 s99, s37, s99
	s_cmp_ge_i32 s63, s99
	s_cselect_b32 s99, 1, 0
	s_and_b32 s98, s98, s99
.Lhl_set:
	v_writelane_b32 v255, s98, 57
	s_cmp_ge_i32 s63, s36
	s_cbranch_scc0 .LBB0_1310
	s_sub_i32 s4, s63, s36
	s_lshl_b32 s7, s63, 8
	s_lshr_b32 s6, s4, 6
	s_and_b32 s83, s7, 0x700
	s_bfe_u32 s20, s63, 0x30003
	s_mul_i32 s5, s6, 0x900
	s_add_i32 s7, s83, 0x100
	s_mul_hi_u32 s4, s6, 0x900
	s_add_u32 s8, s5, s7
	s_addc_u32 s9, s4, 0
	s_add_i32 s4, s83, 0xffffff80
	s_cmp_lg_u32 s83, 0
	s_cselect_b32 s12, s4, 0
	s_min_u32 s10, s83, 0x680
	s_lshl_b64 s[4:5], s[8:9], 13
	s_add_u32 s4, s60, s4
	s_addc_u32 s5, s71, s5
	s_lshl_b32 s7, s20, 7
	s_add_u32 s13, s4, s7
	s_addc_u32 s17, s5, 0
	s_mul_hi_u32 s4, s6, 0x1200000
	s_mul_i32 s6, s6, 0x1200000
	s_add_u32 s5, s60, s6
	s_addc_u32 s4, s71, s4
	s_lshl_b32 s6, s63, 2
	s_and_b32 s6, s6, 0x80
	s_add_u32 s6, s5, s6
	s_addc_u32 s7, s4, 0
	s_load_dwordx2 s[4:5], s[0:1], 0x58
	s_sub_i32 s10, s10, s12
	s_addk_i32 s10, 0x180
	s_or_b32 s40, s20, s70
	s_ashr_i32 s89, s10, 6
	s_lshl_b64 s[10:11], s[40:41], 2
	s_waitcnt lgkmcnt(0)
	s_add_u32 s4, s4, s10
	s_addc_u32 s5, s5, s11
	v_mov_b32_e32 v56, v223
	global_load_dword v228, v1, s[4:5]
	v_mov_b32_e32 v14, v1
	v_readfirstlane_b32 s21, v56
	s_ashr_i32 s40, s21, 6
	s_lshl_b32 s10, s40, 5
	s_ashr_i32 s11, s10, 31
	v_and_b32_e32 v224, 63, v56
	s_lshl_b64 s[4:5], s[10:11], 13
	s_add_u32 s16, s13, s4
	v_lshlrev_b32_e32 v0, 13, v224
	s_addc_u32 s17, s17, s5
	v_lshl_add_u64 v[2:3], s[6:7], 0, v[0:1]
	s_lshl_b32 s5, s40, 4
	v_bfe_u32 v0, v56, 2, 4
	s_lshl_b32 s18, s40, 3
	v_and_or_b32 v0, s5, 48, v0
	s_ashr_i32 s19, s18, 31
	v_lshlrev_b32_e32 v0, 13, v0
	s_ashr_i32 s5, s21, 3
	v_lshl_add_u64 v[96:97], s[18:19], 1, v[2:3]
	v_lshl_add_u64 v[2:3], s[6:7], 0, v[0:1]
	s_and_b32 s6, s5, 0xffffffe0
	s_and_b32 s4, s21, 0x3fffffc0
	s_ashr_i32 s7, s6, 31
	v_lshlrev_b32_e32 v225, 3, v56
	s_lshl_b32 s90, s40, 10
	v_and_b32_e32 v229, 24, v225
	s_cmp_lg_u32 0, -1
	s_mov_b64 s[18:19], 0xa00
	v_lshl_add_u64 v[2:3], s[6:7], 1, v[2:3]
	v_lshlrev_b32_e32 v0, 1, v229
	s_cselect_b32 s5, 0, 0
	v_and_b32_e32 v226, 31, v56
	v_lshl_add_u64 v[202:203], v[96:97], 0, s[18:19]
	v_lshl_add_u64 v[98:99], v[2:3], 0, v[0:1]
	s_mov_b64 s[6:7], 0xb00
	s_add_i32 s90, s90, s5
	s_mov_b32 s5, m0
	s_mov_b32 m0, s90
	s_nop 0
	global_load_lds_dwordx4 v[202:203], off
	s_mov_b32 m0, s5
	v_bfe_u32 v227, v56, 5, 1
	v_lshl_add_u64 v[128:129], v[98:99], 0, s[6:7]
	s_add_i32 s91, s90, 0x6000
	s_mov_b32 s5, m0
	s_mov_b32 m0, s91
	s_nop 0
	global_load_lds_dwordx4 v[128:129], off
	s_mov_b32 m0, s5
	s_mov_b64 s[6:7], 0x80a00
	v_lshlrev_b32_e32 v0, 13, v226
	v_lshl_add_u64 v[2:3], v[96:97], 0, s[6:7]
	s_add_i32 s5, s90, 0x2000
	s_mov_b32 s6, m0
	s_mov_b32 m0, s5
	s_nop 0
	global_load_lds_dwordx4 v[2:3], off
	s_mov_b32 m0, s6
	v_lshl_or_b32 v0, v227, 4, v0
	global_load_dwordx4 v[162:165], v0, s[16:17] offset:1536
	global_load_dwordx4 v[158:161], v0, s[16:17] offset:1568
	global_load_dwordx4 v[154:157], v0, s[16:17] offset:1600
	global_load_dwordx4 v[150:153], v0, s[16:17] offset:1632
	v_lshlrev_b32_e32 v2, 10, v227
	v_lshlrev_b32_e32 v3, 4, v226
	v_mov_b32_e32 v15, v1
	v_add3_u32 v234, 0, v2, v3
	v_mov_b32_e32 v0, v1
	v_mov_b32_e32 v2, v1
	v_mov_b32_e32 v3, v1
	v_mov_b32_e32 v4, v1
	v_mov_b32_e32 v5, v1
	v_mov_b32_e32 v6, v1
	v_mov_b32_e32 v7, v1
	v_mov_b32_e32 v8, v1
	v_mov_b32_e32 v9, v1
	v_mov_b32_e32 v10, v1
	v_mov_b32_e32 v11, v1
	v_mov_b32_e32 v12, v1
	v_mov_b32_e32 v13, v1
	v_mov_b64_e32 v[30:31], v[14:15]
	v_mov_b64_e32 v[28:29], v[12:13]
	v_mov_b64_e32 v[26:27], v[10:11]
	v_mov_b64_e32 v[24:25], v[8:9]
	v_mov_b64_e32 v[22:23], v[6:7]
	v_mov_b64_e32 v[20:21], v[4:5]
	v_mov_b64_e32 v[18:19], v[2:3]
	v_mov_b64_e32 v[16:17], v[0:1]
	s_mov_b64 s[6:7], 0x100a00
	v_lshl_add_u64 v[32:33], v[96:97], 0, s[6:7]
	s_add_i32 s5, s90, 0x4000
	s_mov_b32 s6, m0
	s_mov_b32 m0, s5
	s_nop 0
	global_load_lds_dwordx4 v[32:33], off
	s_mov_b32 m0, s6
	s_waitcnt vmcnt(3) lgkmcnt(0)
	s_barrier
	ds_read_b128 v[48:51], v234
	ds_read_b128 v[52:55], v234 offset:512
	s_waitcnt vmcnt(3) lgkmcnt(1)
	v_mfma_f32_32x32x16_bf16 v[32:47], v[48:51], v[162:165], v[16:31]
	s_lshl_b32 s4, s4, 2
	s_add_i32 s82, s4, 0
	s_mov_b64 s[4:5], 0x180a00
	s_mov_b32 s21, 0
	s_mov_b32 s64, 1
	s_movk_i32 s13, 0x2000
	s_movk_i32 s31, 0x4000
	s_waitcnt lgkmcnt(0)
	v_mfma_f32_32x32x16_bf16 v[16:31], v[52:55], v[162:165], v[16:31]
	ds_read_b128 v[48:51], v234 offset:2048
	ds_read_b128 v[52:55], v234 offset:2560
	v_lshlrev_b32_e32 v236, 4, v227
	v_lshl_add_u32 v233, v226, 2, s82
	v_lshl_add_u32 v206, v227, 2, s12
	s_waitcnt vmcnt(2) lgkmcnt(1)
	v_mfma_f32_32x32x16_bf16 v[32:47], v[48:51], v[158:161], v[32:47]
	s_waitcnt lgkmcnt(0)
	v_mfma_f32_32x32x16_bf16 v[16:31], v[52:55], v[158:161], v[16:31]
	ds_read_b128 v[48:51], v234 offset:4096
	ds_read_b128 v[52:55], v234 offset:4608
	s_waitcnt vmcnt(1) lgkmcnt(1)
	v_mfma_f32_32x32x16_bf16 v[32:47], v[48:51], v[154:157], v[32:47]
	ds_read_b128 v[48:51], v234 offset:6144
	s_waitcnt lgkmcnt(1)
	v_mfma_f32_32x32x16_bf16 v[16:31], v[52:55], v[154:157], v[16:31]
	ds_read_b128 v[52:55], v234 offset:6656
	s_waitcnt vmcnt(0) lgkmcnt(1)
	v_mfma_f32_32x32x16_bf16 v[32:47], v[48:51], v[150:153], v[32:47]
	v_lshlrev_b32_e32 v48, 1, v56
	v_lshlrev_b32_e32 v49, 4, v56
	v_and_b32_e32 v232, 32, v48
	v_and_b32_e32 v48, 0xc0, v49
	v_lshl_or_b32 v231, v227, 8, v48
	v_add_u32_e32 v48, 0, v232
	v_add3_u32 v235, v48, v229, v231
	s_waitcnt lgkmcnt(0)
	v_mfma_f32_32x32x16_bf16 v[16:31], v[52:55], v[150:153], v[16:31]
	s_nop 15
	s_nop 7
	s_nop 0
	v_max3_f32 v49, v32, v33, v16
	v_max3_f32 v50, v34, v35, v17
	s_nop 0
	v_max3_f32 v49, v49, v18, v19
	v_max3_f32 v50, v50, v38, v39
	s_nop 0
	v_max3_f32 v49, v49, v36, v37
	v_max3_f32 v50, v50, v22, v23
	s_nop 0
	v_max3_f32 v49, v49, v20, v21
	v_max3_f32 v50, v50, v42, v43
	s_nop 0
	v_max3_f32 v49, v49, v40, v41
	v_max3_f32 v50, v50, v26, v27
	s_nop 0
	v_max3_f32 v49, v49, v24, v25
	v_max3_f32 v50, v50, v46, v47
	s_nop 0
	v_max3_f32 v49, v49, v44, v45
	v_max3_f32 v50, v50, v30, v31
	s_nop 0
	v_max3_f32 v49, v49, v28, v29
	s_nop 0
	v_max_f32_e32 v49, v49, v50
	s_nop 0
	v_mov_b32_e32 v50, v49
	s_nop 1
	v_permlane32_swap_b32_e32 v49, v50
	v_max_f32_e32 v49, v49, v50
	s_nop 0
	v_add_f32_e32 v230, v1, v49
	v_sub_f32_e32 v32, v32, v49
	v_sub_f32_e32 v16, v16, v49
	v_sub_f32_e32 v33, v33, v49
	v_sub_f32_e32 v17, v17, v49
	v_sub_f32_e32 v34, v34, v49
	s_nop 0
	v_xor_b32_e32 v48, 0x80000000, v230
	v_sub_f32_e32 v18, v18, v49
	v_sub_f32_e32 v35, v35, v49
	v_sub_f32_e32 v19, v19, v49
	v_sub_f32_e32 v36, v36, v49
	v_sub_f32_e32 v20, v20, v49
	v_sub_f32_e32 v37, v37, v49
	v_sub_f32_e32 v21, v21, v49
	v_sub_f32_e32 v38, v38, v49
	v_sub_f32_e32 v22, v22, v49
	v_sub_f32_e32 v39, v39, v49
	v_sub_f32_e32 v23, v23, v49
	v_sub_f32_e32 v40, v40, v49
	v_sub_f32_e32 v24, v24, v49
	v_sub_f32_e32 v41, v41, v49
	v_sub_f32_e32 v25, v25, v49
	v_sub_f32_e32 v42, v42, v49
	v_sub_f32_e32 v26, v26, v49
	v_sub_f32_e32 v43, v43, v49
	v_sub_f32_e32 v27, v27, v49
	v_sub_f32_e32 v44, v44, v49
	v_sub_f32_e32 v28, v28, v49
	v_sub_f32_e32 v45, v45, v49
	v_sub_f32_e32 v29, v29, v49
	v_sub_f32_e32 v46, v46, v49
	v_sub_f32_e32 v30, v30, v49
	v_sub_f32_e32 v47, v47, v49
	v_sub_f32_e32 v31, v31, v49
	v_mov_b32_e32 v49, v48
	v_mov_b32_e32 v50, v48
	v_mov_b32_e32 v51, v48
	v_mov_b32_e32 v52, v48
	v_mov_b32_e32 v53, v48
	v_mov_b32_e32 v54, v48
	v_mov_b32_e32 v55, v48
	v_mov_b32_e32 v56, v48
	v_mov_b32_e32 v57, v48
	v_mov_b32_e32 v58, v48
	v_mov_b32_e32 v59, v48
	v_mov_b32_e32 v60, v48
	v_mov_b32_e32 v61, v48
	v_mov_b32_e32 v62, v48
	v_mov_b32_e32 v63, v48
	s_waitcnt vmcnt(0) lgkmcnt(0)
	s_barrier
	v_exp_f32_e32 v64, v16
	v_exp_f32_e32 v65, v17
	v_lshl_add_u64 v[16:17], v[96:97], 0, s[4:5]
	s_mov_b32 s4, m0
	s_mov_b32 m0, s90
	s_nop 0
	global_load_lds_dwordx4 v[16:17], off
	s_mov_b32 m0, s4
	s_mov_b64 s[4:5], 0x80b00
	v_lshl_add_u64 v[16:17], v[98:99], 0, s[4:5]
	s_add_i32 s4, s90, 0x8000
	s_mov_b32 s5, m0
	s_mov_b32 m0, s4
	s_nop 0
	global_load_lds_dwordx4 v[16:17], off
	s_mov_b32 m0, s5
	ds_read_b128 v[194:197], v234 offset:8192
	ds_read_b128 v[190:193], v234 offset:8704
	ds_read_b128 v[186:189], v234 offset:10240
	ds_read_b128 v[182:185], v234 offset:10752
	ds_read_b128 v[178:181], v234 offset:12288
	ds_read_b128 v[174:177], v234 offset:12800
	ds_read_b128 v[170:173], v234 offset:14336
	ds_read_b128 v[166:169], v234 offset:14848
	v_exp_f32_e32 v80, v32
	v_exp_f32_e32 v81, v33
	v_exp_f32_e32 v82, v34
	v_exp_f32_e32 v83, v35
	v_exp_f32_e32 v84, v36
	v_exp_f32_e32 v85, v37
	v_exp_f32_e32 v86, v38
	v_exp_f32_e32 v87, v39
	v_exp_f32_e32 v88, v40
	v_exp_f32_e32 v89, v41
	v_exp_f32_e32 v90, v42
	v_exp_f32_e32 v91, v43
	v_exp_f32_e32 v92, v44
	v_exp_f32_e32 v93, v45
	v_exp_f32_e32 v94, v46
	v_exp_f32_e32 v95, v47
	v_exp_f32_e32 v66, v18
	v_exp_f32_e32 v67, v19
	v_exp_f32_e32 v68, v20
	v_exp_f32_e32 v69, v21
	v_exp_f32_e32 v70, v22
	v_exp_f32_e32 v71, v23
	v_exp_f32_e32 v72, v24
	v_exp_f32_e32 v73, v25
	v_exp_f32_e32 v74, v26
	v_exp_f32_e32 v75, v27
	v_exp_f32_e32 v76, v28
	v_exp_f32_e32 v77, v29
	v_exp_f32_e32 v78, v30
	v_exp_f32_e32 v79, v31
	s_waitcnt vmcnt(2) lgkmcnt(0)
	s_barrier
	s_cmp_lt_i32 s89, 3
	v_cmp_gt_u32_e64 s[4:5], 32, v224
	s_cbranch_scc1 .LBB0_1249
	s_ashr_i32 s13, s12, 31
	v_sub_u32_e32 v0, v206, v226
	s_lshl_b64 s[6:7], s[12:13], 13
	v_subrev_u32_e32 v0, s10, v0
	v_lshl_add_u64 v[2:3], v[202:203], 0, s[6:7]
	s_mov_b64 s[6:7], 0x280000
	v_mov_b32_e32 v14, v1
	v_mov_b32_e32 v15, v1
	v_subrev_u32_e32 v207, s83, v0
	v_lshl_add_u64 v[204:205], v[2:3], 0, s[6:7]
	v_mov_b32_e32 v0, v1
	v_mov_b32_e32 v2, v1
	v_mov_b32_e32 v3, v1
	v_mov_b32_e32 v4, v1
	v_mov_b32_e32 v5, v1
	v_mov_b32_e32 v6, v1
	v_mov_b32_e32 v7, v1
	v_mov_b32_e32 v8, v1
	v_mov_b32_e32 v9, v1
	v_mov_b32_e32 v10, v1
	v_mov_b32_e32 v11, v1
	v_mov_b32_e32 v12, v1
	v_mov_b32_e32 v13, v1
	v_mov_b64_e32 v[46:47], v[14:15]
	v_mov_b64_e32 v[30:31], v[14:15]
	s_add_i32 s30, s89, -1
	s_mov_b32 s6, 0
	s_movk_i32 s21, 0x4000
	s_movk_i32 s57, 0x2000
	v_mov_b32_e32 v237, 0
	s_movk_i32 s56, 0xc0
	v_mov_b64_e32 v[44:45], v[12:13]
	v_mov_b64_e32 v[42:43], v[10:11]
	v_mov_b64_e32 v[40:41], v[8:9]
	v_mov_b64_e32 v[38:39], v[6:7]
	v_mov_b64_e32 v[36:37], v[4:5]
	v_mov_b64_e32 v[34:35], v[2:3]
	v_mov_b64_e32 v[32:33], v[0:1]
	v_mov_b64_e32 v[28:29], v[12:13]
	v_mov_b64_e32 v[26:27], v[10:11]
	v_mov_b64_e32 v[24:25], v[8:9]
	v_mov_b64_e32 v[22:23], v[6:7]
	v_mov_b64_e32 v[20:21], v[4:5]
	v_mov_b64_e32 v[18:19], v[2:3]
	v_mov_b64_e32 v[16:17], v[0:1]
